# P3b (MLA up-projection) unit loop: drain outstanding epilogue stores / prefetch before entering the main loop, as the out-proj phase already does
# speedup vs baseline: 1.0024x; 1.0020x over previous
; template <class Epi, class Sched>
; __device__ __forceinline__ void gemm_phase(PG8_LAS unsigned char* lds, const Gemm g, const Sched& S, const Epi& E) {
;     ...
; #pragma unroll
;         for (int a = 0; a < 2; ++a)
; #pragma unroll
;             for (int b = 0; b < 2; ++b)
; #pragma unroll
;                 for (int m = 0; m < 4; ++m)
; #pragma unroll
;                     for (int n = 0; n < 2; ++n) acc[a][b][m][n] = (f32x4){0.f, 0.f, 0.f, 0.f};
;         cur = nxt; cA = nA; cB = nB; cnt = ncnt; ++ui;
.LBB0_657:
	s_add_i32 s40, s5, -2
	s_add_u32 s41, s16, 0x100
	v_mov_b32_e32 v2, 0
	s_addc_u32 s42, s17, 0
	s_mov_b32 s20, 0
	v_mov_b32_e32 v3, v2
	v_mov_b32_e32 v4, v2
	v_mov_b32_e32 v5, v2
	v_mov_b32_e32 v10, v2
	v_mov_b32_e32 v11, v2
	v_mov_b32_e32 v12, v2
	v_mov_b32_e32 v13, v2
	v_mov_b32_e32 v18, v2
	v_mov_b32_e32 v19, v2
	v_mov_b32_e32 v20, v2
	v_mov_b32_e32 v21, v2
	v_mov_b32_e32 v26, v2
	v_mov_b32_e32 v27, v2
	v_mov_b32_e32 v28, v2
	v_mov_b32_e32 v29, v2
	v_mov_b32_e32 v34, v2
	v_mov_b32_e32 v35, v2
	v_mov_b32_e32 v36, v2
	v_mov_b32_e32 v37, v2
	v_mov_b32_e32 v42, v2
	v_mov_b32_e32 v43, v2
	v_mov_b32_e32 v44, v2
	v_mov_b32_e32 v45, v2
	v_mov_b32_e32 v50, v2
	v_mov_b32_e32 v51, v2
	v_mov_b32_e32 v52, v2
	v_mov_b32_e32 v53, v2
	v_mov_b32_e32 v58, v2
	v_mov_b32_e32 v59, v2
	v_mov_b32_e32 v60, v2
	v_mov_b32_e32 v61, v2
	v_mov_b32_e32 v6, v2
	v_mov_b32_e32 v7, v2
	v_mov_b32_e32 v8, v2
	v_mov_b32_e32 v9, v2
	v_mov_b32_e32 v14, v2
	v_mov_b32_e32 v15, v2
	v_mov_b32_e32 v16, v2
	v_mov_b32_e32 v17, v2
	v_mov_b32_e32 v22, v2
	v_mov_b32_e32 v23, v2
	v_mov_b32_e32 v24, v2
	v_mov_b32_e32 v25, v2
	v_mov_b32_e32 v30, v2
	v_mov_b32_e32 v31, v2
	v_mov_b32_e32 v32, v2
	v_mov_b32_e32 v33, v2
	v_mov_b32_e32 v38, v2
	v_mov_b32_e32 v39, v2
	v_mov_b32_e32 v40, v2
	v_mov_b32_e32 v41, v2
	v_mov_b32_e32 v46, v2
	v_mov_b32_e32 v47, v2
	v_mov_b32_e32 v48, v2
	v_mov_b32_e32 v49, v2
	v_mov_b32_e32 v54, v2
	v_mov_b32_e32 v55, v2
	v_mov_b32_e32 v56, v2
	v_mov_b32_e32 v57, v2
	v_mov_b32_e32 v62, v2
	v_mov_b32_e32 v63, v2
	v_mov_b32_e32 v64, v2
	v_mov_b32_e32 v65, v2
	v_mov_b32_e32 v66, v2
	v_mov_b32_e32 v67, v2
	v_mov_b32_e32 v68, v2
	v_mov_b32_e32 v69, v2
	v_mov_b32_e32 v74, v2
	v_mov_b32_e32 v75, v2
	v_mov_b32_e32 v76, v2
	v_mov_b32_e32 v77, v2
	v_mov_b32_e32 v82, v2
	v_mov_b32_e32 v83, v2
	v_mov_b32_e32 v84, v2
	v_mov_b32_e32 v85, v2
	v_mov_b32_e32 v90, v2
	v_mov_b32_e32 v91, v2
	v_mov_b32_e32 v92, v2
	v_mov_b32_e32 v93, v2
	v_mov_b32_e32 v98, v2
	v_mov_b32_e32 v99, v2
	v_mov_b32_e32 v100, v2
	v_mov_b32_e32 v101, v2
	v_mov_b32_e32 v106, v2
	v_mov_b32_e32 v107, v2
	v_mov_b32_e32 v108, v2
	v_mov_b32_e32 v109, v2
	v_mov_b32_e32 v114, v2
	v_mov_b32_e32 v115, v2
	v_mov_b32_e32 v116, v2
	v_mov_b32_e32 v117, v2
	v_mov_b32_e32 v122, v2
	v_mov_b32_e32 v123, v2
	v_mov_b32_e32 v124, v2
	v_mov_b32_e32 v125, v2
	v_mov_b32_e32 v70, v2
	v_mov_b32_e32 v71, v2
	v_mov_b32_e32 v72, v2
	v_mov_b32_e32 v73, v2
	v_mov_b32_e32 v78, v2
	v_mov_b32_e32 v79, v2
	v_mov_b32_e32 v80, v2
	v_mov_b32_e32 v81, v2
	v_mov_b32_e32 v86, v2
	v_mov_b32_e32 v87, v2
	v_mov_b32_e32 v88, v2
	v_mov_b32_e32 v89, v2
	v_mov_b32_e32 v94, v2
	v_mov_b32_e32 v95, v2
	v_mov_b32_e32 v96, v2
	v_mov_b32_e32 v97, v2
	v_mov_b32_e32 v102, v2
	v_mov_b32_e32 v103, v2
	v_mov_b32_e32 v104, v2
	v_mov_b32_e32 v105, v2
	v_mov_b32_e32 v110, v2
	v_mov_b32_e32 v111, v2
	v_mov_b32_e32 v112, v2
	v_mov_b32_e32 v113, v2
	v_mov_b32_e32 v118, v2
	v_mov_b32_e32 v119, v2
	v_mov_b32_e32 v120, v2
	v_mov_b32_e32 v121, v2
	v_mov_b32_e32 v126, v2
	v_mov_b32_e32 v127, v2
	v_mov_b32_e32 v128, v2
	v_mov_b32_e32 v129, v2
	s_waitcnt vmcnt(0)
